# GLU GEMM epilogue: the 8 gate-operand loads of each column half requested up front with a counted vmcnt wait (was one block ahead + vmcnt(0) that also drained the output store)
# speedup vs baseline: 1.0012x; 1.0012x over previous
; __device__ __forceinline__ unsigned cvt_pk_bf16(float lo, float hi) { unsigned r; asm volatile("v_cvt_pk_bf16_f32 %0, %1, %2" : "=v"(r) : "v"(lo), "v"(hi)); return r; }
; __device__ __forceinline__ float bf_lo(unsigned w) { return __uint_as_float(w << 16); }
; __device__ __forceinline__ float bf_hi(unsigned w) { return __uint_as_float(w & 0xffff0000u); }
; __device__ __forceinline__ float sigmoid_f(float x) { return __builtin_amdgcn_rcpf(1.0f + __expf(-x)); }
; __device__ __forceinline__ float gelu_t(float x) { const float u = 1.5957691216057308f * (x + 0.044715f * x * x * x); return x * sigmoid_f(u); }
;     __device__ __forceinline__ void operator()(const f32x4 (&acc)[2][2][4][2], const Unit& u, int wr, int wc, int fr, int fq) const {
;     ...
;             const int col = col0 + bj * HALF;
;             f32x4 b0 = (f32x4){0.f, 0.f, 0.f, 0.f}, b1 = b0;
;             if (MODE == 2) { b0 = *(const f32x4*)(bias + col); b1 = *(const f32x4*)(bias + col + 4); }
;             const bool act = (MODE == 1) && (col < act_cols);
; #pragma unroll
;             for (int ai = 0; ai < 2; ++ai)
; #pragma unroll
;                 for (int m = 0; m < 4; ++m) {
;                     const size_t row = (size_t)(row0 + ai * HALF + m * 16);
;                     f32x4 v0 = acc[ai][bj][m][0], v1 = acc[ai][bj][m][1];
;                     if (MODE == 1) { if (act) {
; #pragma unroll
;                         for (int j = 0; j < 4; ++j) { v0[j] = gelu_t(v0[j]); v1[j] = gelu_t(v1[j]); } } }
;                     if (MODE == 2) {
;                         const u32x4 y = *(const u32x4*)(Y + row * ldy + col);
;                         v0 = v0 + b0; v1 = v1 + b1;
;                         v0[0] = bf_lo(y.x) * sigmoid_f(v0[0]); v0[1] = bf_hi(y.x) * sigmoid_f(v0[1]); v0[2] = bf_lo(y.y) * sigmoid_f(v0[2]); v0[3] = bf_hi(y.y) * sigmoid_f(v0[3]);
;                         v1[0] = bf_lo(y.z) * sigmoid_f(v1[0]); v1[1] = bf_hi(y.z) * sigmoid_f(v1[1]); v1[2] = bf_lo(y.w) * sigmoid_f(v1[2]); v1[3] = bf_hi(y.w) * sigmoid_f(v1[3]);
;                     }
;                     u32x4 w; w.x = cvt_pk_bf16(v0[0], v0[1]); w.y = cvt_pk_bf16(v0[2], v0[3]); w.z = cvt_pk_bf16(v1[0], v1[1]); w.w = cvt_pk_bf16(v1[2], v1[3]);
;                     *(u32x4*)(O + row * ldc + col) = w;
.LBB0_763:
	v_lshl_or_b32 v152, s63, 8, v166
	v_ashrrev_i32_e32 v153, 31, v152
	v_lshl_add_u64 v[156:157], v[152:153], 2, s[10:11]
	global_load_dwordx4 v[116:119], v[156:157], off
	global_load_dwordx4 v[112:115], v[156:157], off offset:16
	v_lshl_add_u32 v162, s30, 8, v164
	v_ashrrev_i32_e32 v163, 31, v162
	v_lshlrev_b64 v[154:155], 10, v[162:163]
	v_lshlrev_b64 v[160:161], 1, v[152:153]
	v_lshl_add_u64 v[152:153], s[16:17], 0, v[154:155]
	v_lshl_add_u64 v[158:159], v[152:153], 0, v[160:161]
	global_load_dwordx4 v[170:173], v[158:159], off
	v_mov_b32_e32 v237, 0
	v_mov_b32_e32 v236, 0x4000
	v_lshl_add_u64 v[218:219], v[236:237], 0, v[158:159]
	v_mov_b32_e32 v236, 0x8000
	v_lshl_add_u64 v[220:221], v[236:237], 0, v[158:159]
	v_mov_b32_e32 v236, 0xc000
	v_lshl_add_u64 v[222:223], v[236:237], 0, v[158:159]
	v_mov_b32_e32 v236, 0x20000
	v_lshl_add_u64 v[224:225], v[236:237], 0, v[158:159]
	v_mov_b32_e32 v236, 0x24000
	v_lshl_add_u64 v[226:227], v[236:237], 0, v[158:159]
	v_mov_b32_e32 v236, 0x28000
	v_lshl_add_u64 v[228:229], v[236:237], 0, v[158:159]
	v_mov_b32_e32 v236, 0x2c000
	v_lshl_add_u64 v[234:235], v[236:237], 0, v[158:159]
	global_load_dwordx4 v[190:193], v[218:219], off
	global_load_dwordx4 v[194:197], v[220:221], off
	global_load_dwordx4 v[198:201], v[222:223], off
	global_load_dwordx4 v[202:205], v[224:225], off
	global_load_dwordx4 v[206:209], v[226:227], off
	global_load_dwordx4 v[210:213], v[228:229], off
	global_load_dwordx4 v[214:217], v[234:235], off
	v_or_b32_e32 v174, 16, v162
	v_lshlrev_b64 v[152:153], 11, v[162:163]
	v_ashrrev_i32_e32 v175, 31, v174
	v_lshl_add_u64 v[152:153], s[14:15], 0, v[152:153]
	v_lshlrev_b64 v[154:155], 10, v[174:175]
	v_lshl_add_u64 v[152:153], v[152:153], 0, v[160:161]
	v_lshl_add_u64 v[154:155], s[16:17], 0, v[154:155]
	v_lshl_add_u64 v[154:155], v[154:155], 0, v[160:161]
	s_andn2_b64 vcc, exec, s[8:9]
	s_mov_b64 s[8:9], -1
	s_waitcnt vmcnt(7)
	v_pk_add_f32 v[134:135], v[134:135], v[118:119]
	v_pk_add_f32 v[130:131], v[130:131], v[114:115]
	v_pk_add_f32 v[132:133], v[132:133], v[116:117]
	v_pk_add_f32 v[128:129], v[128:129], v[112:113]
	v_mul_f32_e32 v131, 0xbfb8aa3b, v131
	v_mul_f32_e32 v132, 0xbfb8aa3b, v132
	v_mul_f32_e32 v133, 0xbfb8aa3b, v133
	v_mul_f32_e32 v134, 0xbfb8aa3b, v134
	v_mul_f32_e32 v135, 0xbfb8aa3b, v135
	v_mul_f32_e32 v128, 0xbfb8aa3b, v128
	v_mul_f32_e32 v129, 0xbfb8aa3b, v129
	v_mul_f32_e32 v130, 0xbfb8aa3b, v130
	v_exp_f32_e32 v131, v131
	v_exp_f32_e32 v132, v132
	v_exp_f32_e32 v133, v133
	v_exp_f32_e32 v134, v134
	v_exp_f32_e32 v135, v135
	v_exp_f32_e32 v128, v128
	v_exp_f32_e32 v129, v129
	v_exp_f32_e32 v130, v130
	v_add_f32_e32 v131, 1.0, v131
	v_add_f32_e32 v132, 1.0, v132
	v_add_f32_e32 v133, 1.0, v133
	v_add_f32_e32 v134, 1.0, v134
	v_add_f32_e32 v135, 1.0, v135
	v_add_f32_e32 v128, 1.0, v128
	v_add_f32_e32 v129, 1.0, v129
	v_add_f32_e32 v130, 1.0, v130
	v_rcp_f32_e32 v131, v131
	v_rcp_f32_e32 v132, v132
	v_rcp_f32_e32 v133, v133
	v_rcp_f32_e32 v134, v134
	v_rcp_f32_e32 v135, v135
	v_rcp_f32_e32 v128, v128
	v_rcp_f32_e32 v129, v129
	v_rcp_f32_e32 v130, v130
	v_lshlrev_b32_e32 v178, 16, v173
	v_and_b32_e32 v173, 0xffff0000, v173
	v_lshlrev_b32_e32 v163, 16, v170
	v_and_b32_e32 v170, 0xffff0000, v170
	v_lshlrev_b32_e32 v176, 16, v171
	v_and_b32_e32 v171, 0xffff0000, v171
	v_lshlrev_b32_e32 v177, 16, v172
	v_and_b32_e32 v172, 0xffff0000, v172
	v_mul_f32_e32 v131, v131, v173
	v_mul_f32_e32 v132, v132, v163
	v_mul_f32_e32 v133, v133, v170
	v_mul_f32_e32 v134, v134, v176
	v_mul_f32_e32 v135, v135, v171
	v_mul_f32_e32 v163, v128, v177
	v_mul_f32_e32 v170, v129, v172
	v_mul_f32_e32 v171, v130, v178
	v_cvt_pk_bf16_f32 v128, v132, v133
	v_cvt_pk_bf16_f32 v129, v134, v135
	v_cvt_pk_bf16_f32 v130, v163, v170
	v_cvt_pk_bf16_f32 v131, v171, v131
	global_store_dwordx4 v[152:153], v[128:131], off
	v_pk_add_f32 v[122:123], v[122:123], v[114:115]
	v_pk_add_f32 v[126:127], v[126:127], v[118:119]
	v_pk_add_f32 v[124:125], v[124:125], v[116:117]
	v_pk_add_f32 v[120:121], v[120:121], v[112:113]
	v_mul_f32_e32 v123, 0xbfb8aa3b, v123
	v_mul_f32_e32 v124, 0xbfb8aa3b, v124
	v_mul_f32_e32 v125, 0xbfb8aa3b, v125
	v_mul_f32_e32 v126, 0xbfb8aa3b, v126
	v_mul_f32_e32 v127, 0xbfb8aa3b, v127
	v_mul_f32_e32 v120, 0xbfb8aa3b, v120
	v_mul_f32_e32 v121, 0xbfb8aa3b, v121
	v_mul_f32_e32 v122, 0xbfb8aa3b, v122
	v_exp_f32_e32 v123, v123
	v_exp_f32_e32 v124, v124
	v_exp_f32_e32 v125, v125
	v_exp_f32_e32 v126, v126
	v_exp_f32_e32 v127, v127
	v_exp_f32_e32 v120, v120
	v_exp_f32_e32 v121, v121
	v_exp_f32_e32 v122, v122
	v_add_f32_e32 v123, 1.0, v123
	v_add_f32_e32 v124, 1.0, v124
	v_add_f32_e32 v125, 1.0, v125
	v_add_f32_e32 v126, 1.0, v126
	v_add_f32_e32 v127, 1.0, v127
	v_add_f32_e32 v120, 1.0, v120
	v_add_f32_e32 v121, 1.0, v121
	v_add_f32_e32 v122, 1.0, v122
	v_rcp_f32_e32 v123, v123
	v_or_b32_e32 v170, 32, v162
	v_rcp_f32_e32 v124, v124
	v_rcp_f32_e32 v125, v125
	v_rcp_f32_e32 v126, v126
	v_rcp_f32_e32 v127, v127
	v_rcp_f32_e32 v120, v120
	v_rcp_f32_e32 v121, v121
	v_rcp_f32_e32 v122, v122
	v_ashrrev_i32_e32 v171, 31, v170
	v_lshlrev_b64 v[128:129], 11, v[174:175]
	v_lshlrev_b64 v[130:131], 10, v[170:171]
	v_lshl_add_u64 v[128:129], s[14:15], 0, v[128:129]
	v_lshl_add_u64 v[130:131], s[16:17], 0, v[130:131]
	v_lshl_add_u64 v[128:129], v[128:129], 0, v[160:161]
	v_lshl_add_u64 v[130:131], v[130:131], 0, v[160:161]
	v_pk_add_f32 v[106:107], v[106:107], v[114:115]
	v_pk_add_f32 v[110:111], v[110:111], v[118:119]
	v_pk_add_f32 v[108:109], v[108:109], v[116:117]
	v_pk_add_f32 v[104:105], v[104:105], v[112:113]
	v_mul_f32_e32 v107, 0xbfb8aa3b, v107
	v_mul_f32_e32 v108, 0xbfb8aa3b, v108
	v_mul_f32_e32 v109, 0xbfb8aa3b, v109
	v_mul_f32_e32 v110, 0xbfb8aa3b, v110
	v_mul_f32_e32 v111, 0xbfb8aa3b, v111
	v_mul_f32_e32 v104, 0xbfb8aa3b, v104
	v_mul_f32_e32 v105, 0xbfb8aa3b, v105
	v_mul_f32_e32 v106, 0xbfb8aa3b, v106
	v_exp_f32_e32 v107, v107
	v_exp_f32_e32 v108, v108
	v_exp_f32_e32 v109, v109
	v_exp_f32_e32 v110, v110
	v_exp_f32_e32 v111, v111
	v_exp_f32_e32 v104, v104
	v_exp_f32_e32 v105, v105
	v_exp_f32_e32 v106, v106
	v_add_f32_e32 v107, 1.0, v107
	v_add_f32_e32 v108, 1.0, v108
	v_add_f32_e32 v109, 1.0, v109
	v_add_f32_e32 v110, 1.0, v110
	v_add_f32_e32 v111, 1.0, v111
	v_add_f32_e32 v104, 1.0, v104
	v_add_f32_e32 v105, 1.0, v105
	v_add_f32_e32 v106, 1.0, v106
	v_rcp_f32_e32 v107, v107
	v_rcp_f32_e32 v108, v108
	v_rcp_f32_e32 v109, v109
	v_rcp_f32_e32 v110, v110
	v_rcp_f32_e32 v111, v111
	v_rcp_f32_e32 v104, v104
	v_rcp_f32_e32 v105, v105
	s_waitcnt vmcnt(7)
; __device__ __forceinline__ unsigned cvt_pk_bf16(float lo, float hi) { unsigned r; asm volatile("v_cvt_pk_bf16_f32 %0, %1, %2" : "=v"(r) : "v"(lo), "v"(hi)); return r; }
; __device__ __forceinline__ float bf_lo(unsigned w) { return __uint_as_float(w << 16); }
; __device__ __forceinline__ float bf_hi(unsigned w) { return __uint_as_float(w & 0xffff0000u); }
; __device__ __forceinline__ float sigmoid_f(float x) { return __builtin_amdgcn_rcpf(1.0f + __expf(-x)); }
; __device__ __forceinline__ float gelu_t(float x) { const float u = 1.5957691216057308f * (x + 0.044715f * x * x * x); return x * sigmoid_f(u); }
;     __device__ __forceinline__ void operator()(const f32x4 (&acc)[2][2][4][2], const Unit& u, int wr, int wc, int fr, int fq) const {
;     ...
;                     if (MODE == 1) { if (act) {
; #pragma unroll
;                         for (int j = 0; j < 4; ++j) { v0[j] = gelu_t(v0[j]); v1[j] = gelu_t(v1[j]); } } }
;                     if (MODE == 2) {
;                         const u32x4 y = *(const u32x4*)(Y + row * ldy + col);
;                         v0 = v0 + b0; v1 = v1 + b1;
;                         v0[0] = bf_lo(y.x) * sigmoid_f(v0[0]); v0[1] = bf_hi(y.x) * sigmoid_f(v0[1]); v0[2] = bf_lo(y.y) * sigmoid_f(v0[2]); v0[3] = bf_hi(y.y) * sigmoid_f(v0[3]);
;                         v1[0] = bf_lo(y.z) * sigmoid_f(v1[0]); v1[1] = bf_hi(y.z) * sigmoid_f(v1[1]); v1[2] = bf_lo(y.w) * sigmoid_f(v1[2]); v1[3] = bf_hi(y.w) * sigmoid_f(v1[3]);
;                     }
;                     u32x4 w; w.x = cvt_pk_bf16(v0[0], v0[1]); w.y = cvt_pk_bf16(v0[2], v0[3]); w.z = cvt_pk_bf16(v1[0], v1[1]); w.w = cvt_pk_bf16(v1[2], v1[3]);
;                     *(u32x4*)(O + row * ldc + col) = w;
	v_lshlrev_b32_e32 v174, 16, v193
	v_and_b32_e32 v135, 0xffff0000, v193
	v_lshlrev_b32_e32 v163, 16, v190
	v_and_b32_e32 v132, 0xffff0000, v190
	v_lshlrev_b32_e32 v172, 16, v191
	v_and_b32_e32 v133, 0xffff0000, v191
	v_lshlrev_b32_e32 v173, 16, v192
	v_and_b32_e32 v134, 0xffff0000, v192
	v_mul_f32_e32 v123, v123, v135
	v_mul_f32_e32 v124, v124, v163
	v_mul_f32_e32 v125, v125, v132
	v_mul_f32_e32 v126, v126, v172
	v_mul_f32_e32 v127, v127, v133
	v_mul_f32_e32 v132, v120, v173
	v_mul_f32_e32 v133, v121, v134
	v_mul_f32_e32 v134, v122, v174
	v_cvt_pk_bf16_f32 v120, v124, v125
	v_cvt_pk_bf16_f32 v121, v126, v127
	v_cvt_pk_bf16_f32 v122, v132, v133
	v_cvt_pk_bf16_f32 v123, v134, v123
	global_store_dwordx4 v[128:129], v[120:123], off
	v_or_b32_e32 v132, 48, v162
	v_rcp_f32_e32 v106, v106
	v_ashrrev_i32_e32 v133, 31, v132
	v_lshlrev_b64 v[120:121], 11, v[170:171]
	v_lshlrev_b64 v[122:123], 10, v[132:133]
	v_lshl_add_u64 v[120:121], s[14:15], 0, v[120:121]
	v_lshl_add_u64 v[122:123], s[16:17], 0, v[122:123]
	v_lshl_add_u64 v[120:121], v[120:121], 0, v[160:161]
	v_lshl_add_u64 v[122:123], v[122:123], 0, v[160:161]
	v_pk_add_f32 v[98:99], v[98:99], v[114:115]
	v_pk_add_f32 v[102:103], v[102:103], v[118:119]
	v_pk_add_f32 v[100:101], v[100:101], v[116:117]
	v_pk_add_f32 v[96:97], v[96:97], v[112:113]
	v_mul_f32_e32 v99, 0xbfb8aa3b, v99
	v_mul_f32_e32 v100, 0xbfb8aa3b, v100
	v_mul_f32_e32 v101, 0xbfb8aa3b, v101
	v_mul_f32_e32 v102, 0xbfb8aa3b, v102
	v_mul_f32_e32 v103, 0xbfb8aa3b, v103
	v_mul_f32_e32 v96, 0xbfb8aa3b, v96
	v_mul_f32_e32 v97, 0xbfb8aa3b, v97
	v_mul_f32_e32 v98, 0xbfb8aa3b, v98
	v_exp_f32_e32 v99, v99
	v_exp_f32_e32 v100, v100
	v_exp_f32_e32 v101, v101
	v_exp_f32_e32 v102, v102
	v_exp_f32_e32 v103, v103
	v_exp_f32_e32 v96, v96
	v_exp_f32_e32 v97, v97
	v_exp_f32_e32 v98, v98
	v_add_f32_e32 v99, 1.0, v99
	v_add_f32_e32 v100, 1.0, v100
	v_add_f32_e32 v101, 1.0, v101
	v_add_f32_e32 v102, 1.0, v102
	v_add_f32_e32 v103, 1.0, v103
	v_add_f32_e32 v96, 1.0, v96
	v_add_f32_e32 v97, 1.0, v97
	v_add_f32_e32 v98, 1.0, v98
	v_rcp_f32_e32 v99, v99
	v_rcp_f32_e32 v100, v100
	v_rcp_f32_e32 v101, v101
	v_rcp_f32_e32 v102, v102
	v_rcp_f32_e32 v103, v103
	v_rcp_f32_e32 v96, v96
	v_rcp_f32_e32 v97, v97
	v_rcp_f32_e32 v98, v98
	v_pk_add_f32 v[90:91], v[90:91], v[114:115]
	v_pk_add_f32 v[94:95], v[94:95], v[118:119]
	v_pk_add_f32 v[92:93], v[92:93], v[116:117]
	v_pk_add_f32 v[88:89], v[88:89], v[112:113]
	v_mul_f32_e32 v91, 0xbfb8aa3b, v91
	v_mul_f32_e32 v92, 0xbfb8aa3b, v92
	v_mul_f32_e32 v93, 0xbfb8aa3b, v93
	v_mul_f32_e32 v94, 0xbfb8aa3b, v94
	v_mul_f32_e32 v95, 0xbfb8aa3b, v95
	v_mul_f32_e32 v88, 0xbfb8aa3b, v88
	v_mul_f32_e32 v89, 0xbfb8aa3b, v89
	v_mul_f32_e32 v90, 0xbfb8aa3b, v90
	v_exp_f32_e32 v91, v91
	v_exp_f32_e32 v92, v92
	v_exp_f32_e32 v93, v93
	v_exp_f32_e32 v94, v94
	v_exp_f32_e32 v95, v95
	v_exp_f32_e32 v88, v88
	v_exp_f32_e32 v89, v89
	v_exp_f32_e32 v90, v90
	v_add_f32_e32 v91, 1.0, v91
	v_add_f32_e32 v92, 1.0, v92
	v_add_f32_e32 v93, 1.0, v93
	v_add_f32_e32 v94, 1.0, v94
	v_add_f32_e32 v95, 1.0, v95
	v_add_f32_e32 v88, 1.0, v88
	v_add_f32_e32 v89, 1.0, v89
	v_add_f32_e32 v90, 1.0, v90
	v_rcp_f32_e32 v91, v91
	v_rcp_f32_e32 v92, v92
	v_rcp_f32_e32 v93, v93
	v_rcp_f32_e32 v94, v94
	v_rcp_f32_e32 v95, v95
	v_rcp_f32_e32 v88, v88
	s_waitcnt vmcnt(7)
	v_lshlrev_b32_e32 v170, 16, v197
	v_and_b32_e32 v127, 0xffff0000, v197
	v_lshlrev_b32_e32 v134, 16, v194
	v_and_b32_e32 v124, 0xffff0000, v194
	v_lshlrev_b32_e32 v135, 16, v195
	v_and_b32_e32 v125, 0xffff0000, v195
	v_lshlrev_b32_e32 v163, 16, v196
	v_and_b32_e32 v126, 0xffff0000, v196
	v_mul_f32_e32 v107, v107, v127
	v_mul_f32_e32 v108, v108, v134
	v_mul_f32_e32 v109, v109, v124
	v_mul_f32_e32 v110, v110, v135
	v_mul_f32_e32 v111, v111, v125
	v_mul_f32_e32 v124, v104, v163
	v_mul_f32_e32 v125, v105, v126
	v_mul_f32_e32 v126, v106, v170
	v_cvt_pk_bf16_f32 v104, v108, v109
	v_cvt_pk_bf16_f32 v105, v110, v111
	v_cvt_pk_bf16_f32 v106, v124, v125
	v_cvt_pk_bf16_f32 v107, v126, v107
	global_store_dwordx4 v[120:121], v[104:107], off
	v_add_u32_e32 v124, 0x80, v162
	v_ashrrev_i32_e32 v125, 31, v124
	v_lshlrev_b64 v[104:105], 11, v[132:133]
	v_lshlrev_b64 v[106:107], 10, v[124:125]
	v_lshl_add_u64 v[104:105], s[14:15], 0, v[104:105]
	v_lshl_add_u64 v[106:107], s[16:17], 0, v[106:107]
	v_lshl_add_u64 v[104:105], v[104:105], 0, v[160:161]
	v_lshl_add_u64 v[106:107], v[106:107], 0, v[160:161]
	v_rcp_f32_e32 v89, v89
	v_rcp_f32_e32 v90, v90
	v_pk_add_f32 v[82:83], v[82:83], v[114:115]
	v_pk_add_f32 v[86:87], v[86:87], v[118:119]
	v_pk_add_f32 v[84:85], v[84:85], v[116:117]
	v_pk_add_f32 v[80:81], v[80:81], v[112:113]
	v_mul_f32_e32 v83, 0xbfb8aa3b, v83
	v_mul_f32_e32 v84, 0xbfb8aa3b, v84
	v_mul_f32_e32 v85, 0xbfb8aa3b, v85
	v_mul_f32_e32 v86, 0xbfb8aa3b, v86
	v_mul_f32_e32 v87, 0xbfb8aa3b, v87
	v_mul_f32_e32 v80, 0xbfb8aa3b, v80
	v_mul_f32_e32 v81, 0xbfb8aa3b, v81
	v_mul_f32_e32 v82, 0xbfb8aa3b, v82
	v_exp_f32_e32 v83, v83
	v_exp_f32_e32 v84, v84
	v_exp_f32_e32 v85, v85
	v_exp_f32_e32 v86, v86
	v_exp_f32_e32 v87, v87
	v_exp_f32_e32 v80, v80
	v_exp_f32_e32 v81, v81
	v_exp_f32_e32 v82, v82
	v_add_f32_e32 v83, 1.0, v83
	v_add_f32_e32 v84, 1.0, v84
	v_add_f32_e32 v85, 1.0, v85
	v_add_f32_e32 v86, 1.0, v86
	v_add_f32_e32 v87, 1.0, v87
	v_add_f32_e32 v80, 1.0, v80
	v_add_f32_e32 v81, 1.0, v81
	v_add_f32_e32 v82, 1.0, v82
	v_rcp_f32_e32 v83, v83
	v_rcp_f32_e32 v84, v84
	v_rcp_f32_e32 v85, v85
	v_rcp_f32_e32 v86, v86
	v_rcp_f32_e32 v87, v87
	v_rcp_f32_e32 v80, v80
	v_rcp_f32_e32 v81, v81
	v_rcp_f32_e32 v82, v82
	v_pk_add_f32 v[74:75], v[74:75], v[114:115]
	v_pk_add_f32 v[78:79], v[78:79], v[118:119]
	v_pk_add_f32 v[76:77], v[76:77], v[116:117]
	v_pk_add_f32 v[72:73], v[72:73], v[112:113]
	v_mul_f32_e32 v75, 0xbfb8aa3b, v75
	v_mul_f32_e32 v76, 0xbfb8aa3b, v76
	v_mul_f32_e32 v77, 0xbfb8aa3b, v77
	v_mul_f32_e32 v78, 0xbfb8aa3b, v78
	v_mul_f32_e32 v79, 0xbfb8aa3b, v79
	v_mul_f32_e32 v72, 0xbfb8aa3b, v72
	v_mul_f32_e32 v73, 0xbfb8aa3b, v73
	v_mul_f32_e32 v74, 0xbfb8aa3b, v74
	v_exp_f32_e32 v75, v75
	v_exp_f32_e32 v76, v76
	v_exp_f32_e32 v77, v77
	v_exp_f32_e32 v78, v78
	v_exp_f32_e32 v79, v79
	v_exp_f32_e32 v72, v72
	v_exp_f32_e32 v73, v73
	v_exp_f32_e32 v74, v74
	v_add_f32_e32 v75, 1.0, v75
	v_add_f32_e32 v76, 1.0, v76
	v_add_f32_e32 v77, 1.0, v77
	v_add_f32_e32 v78, 1.0, v78
	v_add_f32_e32 v79, 1.0, v79
	v_add_f32_e32 v72, 1.0, v72
	v_add_f32_e32 v73, 1.0, v73
	v_add_f32_e32 v74, 1.0, v74
	v_rcp_f32_e32 v75, v75
	v_rcp_f32_e32 v76, v76
	v_rcp_f32_e32 v77, v77
	v_rcp_f32_e32 v78, v78
	v_rcp_f32_e32 v79, v79
	s_waitcnt vmcnt(7)
; __device__ __forceinline__ unsigned cvt_pk_bf16(float lo, float hi) { unsigned r; asm volatile("v_cvt_pk_bf16_f32 %0, %1, %2" : "=v"(r) : "v"(lo), "v"(hi)); return r; }
; __device__ __forceinline__ float bf_lo(unsigned w) { return __uint_as_float(w << 16); }
; __device__ __forceinline__ float bf_hi(unsigned w) { return __uint_as_float(w & 0xffff0000u); }
; __device__ __forceinline__ float sigmoid_f(float x) { return __builtin_amdgcn_rcpf(1.0f + __expf(-x)); }
; __device__ __forceinline__ float gelu_t(float x) { const float u = 1.5957691216057308f * (x + 0.044715f * x * x * x); return x * sigmoid_f(u); }
;     __device__ __forceinline__ void operator()(const f32x4 (&acc)[2][2][4][2], const Unit& u, int wr, int wc, int fr, int fq) const {
;     ...
;                     if (MODE == 1) { if (act) {
; #pragma unroll
;                         for (int j = 0; j < 4; ++j) { v0[j] = gelu_t(v0[j]); v1[j] = gelu_t(v1[j]); } } }
;                     if (MODE == 2) {
;                         const u32x4 y = *(const u32x4*)(Y + row * ldy + col);
;                         v0 = v0 + b0; v1 = v1 + b1;
;                         v0[0] = bf_lo(y.x) * sigmoid_f(v0[0]); v0[1] = bf_hi(y.x) * sigmoid_f(v0[1]); v0[2] = bf_lo(y.y) * sigmoid_f(v0[2]); v0[3] = bf_hi(y.y) * sigmoid_f(v0[3]);
;                         v1[0] = bf_lo(y.z) * sigmoid_f(v1[0]); v1[1] = bf_hi(y.z) * sigmoid_f(v1[1]); v1[2] = bf_lo(y.w) * sigmoid_f(v1[2]); v1[3] = bf_hi(y.w) * sigmoid_f(v1[3]);
;                     }
;                     u32x4 w; w.x = cvt_pk_bf16(v0[0], v0[1]); w.y = cvt_pk_bf16(v0[2], v0[3]); w.z = cvt_pk_bf16(v1[0], v1[1]); w.w = cvt_pk_bf16(v1[2], v1[3]);
;                     *(u32x4*)(O + row * ldc + col) = w;
	v_lshlrev_b32_e32 v133, 16, v201
	v_and_b32_e32 v111, 0xffff0000, v201
	v_lshlrev_b32_e32 v126, 16, v198
	v_and_b32_e32 v108, 0xffff0000, v198
	v_lshlrev_b32_e32 v127, 16, v199
	v_and_b32_e32 v109, 0xffff0000, v199
	v_lshlrev_b32_e32 v132, 16, v200
	v_and_b32_e32 v110, 0xffff0000, v200
	v_mul_f32_e32 v99, v99, v111
	v_mul_f32_e32 v100, v100, v126
	v_mul_f32_e32 v101, v101, v108
	v_mul_f32_e32 v102, v102, v127
	v_mul_f32_e32 v103, v103, v109
	v_mul_f32_e32 v108, v96, v132
	v_mul_f32_e32 v109, v97, v110
	v_mul_f32_e32 v110, v98, v133
	v_cvt_pk_bf16_f32 v96, v100, v101
	v_cvt_pk_bf16_f32 v97, v102, v103
	v_cvt_pk_bf16_f32 v98, v108, v109
	v_cvt_pk_bf16_f32 v99, v110, v99
	global_store_dwordx4 v[104:105], v[96:99], off
	v_add_u32_e32 v108, 0x90, v162
	v_ashrrev_i32_e32 v109, 31, v108
	v_lshlrev_b64 v[96:97], 11, v[124:125]
	v_lshlrev_b64 v[98:99], 10, v[108:109]
	v_lshl_add_u64 v[96:97], s[14:15], 0, v[96:97]
	v_lshl_add_u64 v[98:99], s[16:17], 0, v[98:99]
	v_lshl_add_u64 v[96:97], v[96:97], 0, v[160:161]
	v_lshl_add_u64 v[98:99], v[98:99], 0, v[160:161]
	v_rcp_f32_e32 v72, v72
	v_rcp_f32_e32 v73, v73
	v_rcp_f32_e32 v74, v74
	v_pk_add_f32 v[66:67], v[66:67], v[114:115]
	v_pk_add_f32 v[70:71], v[70:71], v[118:119]
	v_pk_add_f32 v[68:69], v[68:69], v[116:117]
	v_pk_add_f32 v[64:65], v[64:65], v[112:113]
	v_mul_f32_e32 v67, 0xbfb8aa3b, v67
	v_mul_f32_e32 v68, 0xbfb8aa3b, v68
	v_mul_f32_e32 v69, 0xbfb8aa3b, v69
	v_mul_f32_e32 v70, 0xbfb8aa3b, v70
	v_mul_f32_e32 v71, 0xbfb8aa3b, v71
	v_mul_f32_e32 v64, 0xbfb8aa3b, v64
	v_mul_f32_e32 v65, 0xbfb8aa3b, v65
	v_mul_f32_e32 v66, 0xbfb8aa3b, v66
	v_exp_f32_e32 v67, v67
	v_exp_f32_e32 v68, v68
	v_exp_f32_e32 v69, v69
	v_exp_f32_e32 v70, v70
	v_exp_f32_e32 v71, v71
	v_exp_f32_e32 v64, v64
	v_exp_f32_e32 v65, v65
	v_exp_f32_e32 v66, v66
	v_add_f32_e32 v67, 1.0, v67
	v_add_f32_e32 v68, 1.0, v68
	v_add_f32_e32 v69, 1.0, v69
	v_add_f32_e32 v70, 1.0, v70
	v_add_f32_e32 v71, 1.0, v71
	v_add_f32_e32 v64, 1.0, v64
	v_add_f32_e32 v65, 1.0, v65
	v_add_f32_e32 v66, 1.0, v66
	v_rcp_f32_e32 v67, v67
	v_rcp_f32_e32 v68, v68
	v_rcp_f32_e32 v69, v69
	v_rcp_f32_e32 v70, v70
	v_rcp_f32_e32 v71, v71
	v_rcp_f32_e32 v64, v64
	v_rcp_f32_e32 v65, v65
	v_rcp_f32_e32 v66, v66
	s_waitcnt vmcnt(7)
	v_lshlrev_b32_e32 v125, 16, v205
	v_and_b32_e32 v103, 0xffff0000, v205
	v_lshlrev_b32_e32 v110, 16, v202
	v_and_b32_e32 v100, 0xffff0000, v202
	v_lshlrev_b32_e32 v111, 16, v203
	v_and_b32_e32 v101, 0xffff0000, v203
	v_lshlrev_b32_e32 v124, 16, v204
	v_and_b32_e32 v102, 0xffff0000, v204
	v_mul_f32_e32 v91, v91, v103
	v_mul_f32_e32 v92, v92, v110
	v_mul_f32_e32 v93, v93, v100
	v_mul_f32_e32 v94, v94, v111
	v_mul_f32_e32 v95, v95, v101
	v_mul_f32_e32 v100, v88, v124
	v_mul_f32_e32 v101, v89, v102
	v_mul_f32_e32 v102, v90, v125
	v_cvt_pk_bf16_f32 v88, v92, v93
	v_cvt_pk_bf16_f32 v89, v94, v95
	v_cvt_pk_bf16_f32 v90, v100, v101
	v_cvt_pk_bf16_f32 v91, v102, v91
	global_store_dwordx4 v[96:97], v[88:91], off
	v_add_u32_e32 v100, 0xa0, v162
	v_ashrrev_i32_e32 v101, 31, v100
	v_lshlrev_b64 v[88:89], 11, v[108:109]
	v_lshlrev_b64 v[90:91], 10, v[100:101]
	v_lshl_add_u64 v[88:89], s[14:15], 0, v[88:89]
	v_lshl_add_u64 v[90:91], s[16:17], 0, v[90:91]
	v_lshl_add_u64 v[88:89], v[88:89], 0, v[160:161]
	v_lshl_add_u64 v[90:91], v[90:91], 0, v[160:161]
	s_waitcnt vmcnt(7)
	v_lshlrev_b32_e32 v109, 16, v209
	v_and_b32_e32 v95, 0xffff0000, v209
	v_lshlrev_b32_e32 v102, 16, v206
	v_and_b32_e32 v92, 0xffff0000, v206
	v_lshlrev_b32_e32 v103, 16, v207
	v_and_b32_e32 v93, 0xffff0000, v207
	v_lshlrev_b32_e32 v108, 16, v208
	v_and_b32_e32 v94, 0xffff0000, v208
	v_mul_f32_e32 v83, v83, v95
	v_mul_f32_e32 v84, v84, v102
	v_mul_f32_e32 v85, v85, v92
	v_mul_f32_e32 v86, v86, v103
	v_mul_f32_e32 v87, v87, v93
	v_mul_f32_e32 v92, v80, v108
	v_mul_f32_e32 v93, v81, v94
	v_mul_f32_e32 v94, v82, v109
	v_cvt_pk_bf16_f32 v80, v84, v85
	v_cvt_pk_bf16_f32 v81, v86, v87
	v_cvt_pk_bf16_f32 v82, v92, v93
	v_cvt_pk_bf16_f32 v83, v94, v83
	global_store_dwordx4 v[88:89], v[80:83], off
	v_add_u32_e32 v92, 0xb0, v162
	v_ashrrev_i32_e32 v93, 31, v92
	v_lshlrev_b64 v[80:81], 11, v[100:101]
	v_lshlrev_b64 v[82:83], 10, v[92:93]
	v_lshl_add_u64 v[80:81], s[14:15], 0, v[80:81]
	v_lshl_add_u64 v[82:83], s[16:17], 0, v[82:83]
	v_lshl_add_u64 v[80:81], v[80:81], 0, v[160:161]
	v_lshl_add_u64 v[82:83], v[82:83], 0, v[160:161]
	s_waitcnt vmcnt(7)
	v_lshlrev_b32_e32 v101, 16, v213
	v_and_b32_e32 v87, 0xffff0000, v213
	v_lshlrev_b32_e32 v94, 16, v210
	v_and_b32_e32 v84, 0xffff0000, v210
	v_lshlrev_b32_e32 v95, 16, v211
	v_and_b32_e32 v85, 0xffff0000, v211
	v_lshlrev_b32_e32 v100, 16, v212
	v_and_b32_e32 v86, 0xffff0000, v212
	v_mul_f32_e32 v75, v75, v87
	v_mul_f32_e32 v76, v76, v94
	v_mul_f32_e32 v77, v77, v84
	v_mul_f32_e32 v78, v78, v95
	v_mul_f32_e32 v79, v79, v85
	v_mul_f32_e32 v84, v72, v100
	v_mul_f32_e32 v85, v73, v86
	v_mul_f32_e32 v86, v74, v101
	v_cvt_pk_bf16_f32 v72, v76, v77
	v_cvt_pk_bf16_f32 v73, v78, v79
	v_cvt_pk_bf16_f32 v74, v84, v85
	v_cvt_pk_bf16_f32 v75, v86, v75
	global_store_dwordx4 v[80:81], v[72:75], off
	s_waitcnt vmcnt(7)
; __device__ __forceinline__ unsigned cvt_pk_bf16(float lo, float hi) { unsigned r; asm volatile("v_cvt_pk_bf16_f32 %0, %1, %2" : "=v"(r) : "v"(lo), "v"(hi)); return r; }
; __device__ __forceinline__ float bf_lo(unsigned w) { return __uint_as_float(w << 16); }
; __device__ __forceinline__ float bf_hi(unsigned w) { return __uint_as_float(w & 0xffff0000u); }
; __device__ __forceinline__ float sigmoid_f(float x) { return __builtin_amdgcn_rcpf(1.0f + __expf(-x)); }
; __device__ __forceinline__ float gelu_t(float x) { const float u = 1.5957691216057308f * (x + 0.044715f * x * x * x); return x * sigmoid_f(u); }
;     __device__ __forceinline__ void operator()(const f32x4 (&acc)[2][2][4][2], const Unit& u, int wr, int wc, int fr, int fq) const {
;     ...
;             const int col = col0 + bj * HALF;
;             f32x4 b0 = (f32x4){0.f, 0.f, 0.f, 0.f}, b1 = b0;
;             if (MODE == 2) { b0 = *(const f32x4*)(bias + col); b1 = *(const f32x4*)(bias + col + 4); }
;             const bool act = (MODE == 1) && (col < act_cols);
; #pragma unroll
;             for (int ai = 0; ai < 2; ++ai)
; #pragma unroll
;                 for (int m = 0; m < 4; ++m) {
;                     const size_t row = (size_t)(row0 + ai * HALF + m * 16);
;                     f32x4 v0 = acc[ai][bj][m][0], v1 = acc[ai][bj][m][1];
;                     if (MODE == 1) { if (act) {
; #pragma unroll
;                         for (int j = 0; j < 4; ++j) { v0[j] = gelu_t(v0[j]); v1[j] = gelu_t(v1[j]); } } }
;                     if (MODE == 2) {
;                         const u32x4 y = *(const u32x4*)(Y + row * ldy + col);
;                         v0 = v0 + b0; v1 = v1 + b1;
;                         v0[0] = bf_lo(y.x) * sigmoid_f(v0[0]); v0[1] = bf_hi(y.x) * sigmoid_f(v0[1]); v0[2] = bf_lo(y.y) * sigmoid_f(v0[2]); v0[3] = bf_hi(y.y) * sigmoid_f(v0[3]);
;                         v1[0] = bf_lo(y.z) * sigmoid_f(v1[0]); v1[1] = bf_hi(y.z) * sigmoid_f(v1[1]); v1[2] = bf_lo(y.w) * sigmoid_f(v1[2]); v1[3] = bf_hi(y.w) * sigmoid_f(v1[3]);
;                     }
;                     u32x4 w; w.x = cvt_pk_bf16(v0[0], v0[1]); w.y = cvt_pk_bf16(v0[2], v0[3]); w.z = cvt_pk_bf16(v1[0], v1[1]); w.w = cvt_pk_bf16(v1[2], v1[3]);
;                     *(u32x4*)(O + row * ldc + col) = w;
	v_lshlrev_b32_e32 v85, 16, v217
	v_lshlrev_b64 v[72:73], 11, v[92:93]
	v_lshl_add_u64 v[72:73], s[14:15], 0, v[72:73]
	v_and_b32_e32 v77, 0xffff0000, v217
	v_lshl_add_u64 v[72:73], v[72:73], 0, v[160:161]
	v_lshlrev_b32_e32 v78, 16, v214
	v_and_b32_e32 v74, 0xffff0000, v214
	v_lshlrev_b32_e32 v79, 16, v215
	v_and_b32_e32 v75, 0xffff0000, v215
	v_lshlrev_b32_e32 v84, 16, v216
	v_and_b32_e32 v76, 0xffff0000, v216
	v_mul_f32_e32 v67, v67, v77
	v_mul_f32_e32 v68, v68, v78
	v_mul_f32_e32 v69, v69, v74
	v_mul_f32_e32 v70, v70, v79
	v_mul_f32_e32 v71, v71, v75
	v_mul_f32_e32 v74, v64, v84
	v_mul_f32_e32 v75, v65, v76
	v_mul_f32_e32 v76, v66, v85
	v_cvt_pk_bf16_f32 v64, v68, v69
	v_cvt_pk_bf16_f32 v65, v70, v71
	v_cvt_pk_bf16_f32 v66, v74, v75
	v_cvt_pk_bf16_f32 v67, v76, v67
	global_store_dwordx4 v[72:73], v[64:67], off
	global_load_dwordx4 v[68:71], v[156:157], off offset:512
	s_nop 0
	global_load_dwordx4 v[64:67], v[156:157], off offset:528
	global_load_dwordx4 v[74:77], v[158:159], off offset:256
	global_load_dwordx4 v[190:193], v[218:219], off offset:256
	global_load_dwordx4 v[194:197], v[220:221], off offset:256
	global_load_dwordx4 v[198:201], v[222:223], off offset:256
	global_load_dwordx4 v[202:205], v[224:225], off offset:256
	global_load_dwordx4 v[206:209], v[226:227], off offset:256
	global_load_dwordx4 v[210:213], v[228:229], off offset:256
	global_load_dwordx4 v[214:217], v[234:235], off offset:256
	s_waitcnt vmcnt(9)
	v_pk_add_f32 v[62:63], v[62:63], v[70:71]
	s_waitcnt vmcnt(8)
	v_pk_add_f32 v[58:59], v[58:59], v[66:67]
	v_pk_add_f32 v[60:61], v[60:61], v[68:69]
	v_pk_add_f32 v[56:57], v[56:57], v[64:65]
	v_mul_f32_e32 v59, 0xbfb8aa3b, v59
	v_mul_f32_e32 v60, 0xbfb8aa3b, v60
	v_mul_f32_e32 v61, 0xbfb8aa3b, v61
	v_mul_f32_e32 v62, 0xbfb8aa3b, v62
	v_mul_f32_e32 v63, 0xbfb8aa3b, v63
	v_mul_f32_e32 v56, 0xbfb8aa3b, v56
	v_mul_f32_e32 v57, 0xbfb8aa3b, v57
	v_mul_f32_e32 v58, 0xbfb8aa3b, v58
	v_exp_f32_e32 v59, v59
	v_exp_f32_e32 v60, v60
	v_exp_f32_e32 v61, v61
	v_exp_f32_e32 v62, v62
	v_exp_f32_e32 v63, v63
	v_exp_f32_e32 v56, v56
	v_exp_f32_e32 v57, v57
	v_exp_f32_e32 v58, v58
	v_add_f32_e32 v59, 1.0, v59
	v_add_f32_e32 v60, 1.0, v60
	v_add_f32_e32 v61, 1.0, v61
	v_add_f32_e32 v62, 1.0, v62
	v_add_f32_e32 v63, 1.0, v63
	v_add_f32_e32 v56, 1.0, v56
	v_add_f32_e32 v57, 1.0, v57
	v_add_f32_e32 v58, 1.0, v58
	v_rcp_f32_e32 v59, v59
	v_rcp_f32_e32 v60, v60
	v_rcp_f32_e32 v61, v61
	v_rcp_f32_e32 v62, v62
	v_rcp_f32_e32 v63, v63
	v_rcp_f32_e32 v56, v56
	v_rcp_f32_e32 v57, v57
	v_rcp_f32_e32 v58, v58
	s_waitcnt vmcnt(7)
	v_lshlrev_b32_e32 v85, 16, v77
	v_and_b32_e32 v77, 0xffff0000, v77
	v_lshlrev_b32_e32 v78, 16, v74
	v_and_b32_e32 v74, 0xffff0000, v74
	v_lshlrev_b32_e32 v79, 16, v75
	v_and_b32_e32 v75, 0xffff0000, v75
	v_lshlrev_b32_e32 v84, 16, v76
	v_and_b32_e32 v76, 0xffff0000, v76
	v_mul_f32_e32 v59, v59, v77
	v_mul_f32_e32 v60, v60, v78
	v_mul_f32_e32 v61, v61, v74
	v_mul_f32_e32 v62, v62, v79
	v_mul_f32_e32 v63, v63, v75
	v_mul_f32_e32 v74, v56, v84
	v_mul_f32_e32 v75, v57, v76
	v_mul_f32_e32 v76, v58, v85
	v_cvt_pk_bf16_f32 v56, v60, v61
	v_cvt_pk_bf16_f32 v57, v62, v63
	v_cvt_pk_bf16_f32 v58, v74, v75
	v_cvt_pk_bf16_f32 v59, v76, v59
	global_store_dwordx4 v[152:153], v[56:59], off offset:256
	v_pk_add_f32 v[50:51], v[50:51], v[66:67]
	v_pk_add_f32 v[54:55], v[54:55], v[70:71]
	v_pk_add_f32 v[52:53], v[52:53], v[68:69]
	v_pk_add_f32 v[48:49], v[48:49], v[64:65]
	v_mul_f32_e32 v51, 0xbfb8aa3b, v51
	v_mul_f32_e32 v52, 0xbfb8aa3b, v52
	v_mul_f32_e32 v53, 0xbfb8aa3b, v53
	v_mul_f32_e32 v54, 0xbfb8aa3b, v54
	v_mul_f32_e32 v55, 0xbfb8aa3b, v55
	v_mul_f32_e32 v48, 0xbfb8aa3b, v48
	v_mul_f32_e32 v49, 0xbfb8aa3b, v49
	v_mul_f32_e32 v50, 0xbfb8aa3b, v50
	v_exp_f32_e32 v51, v51
	v_exp_f32_e32 v52, v52
	v_exp_f32_e32 v53, v53
	v_exp_f32_e32 v54, v54
	v_exp_f32_e32 v55, v55
	v_exp_f32_e32 v48, v48
	v_exp_f32_e32 v49, v49
	v_exp_f32_e32 v50, v50
	v_add_f32_e32 v51, 1.0, v51
	v_add_f32_e32 v52, 1.0, v52
	v_add_f32_e32 v53, 1.0, v53
	v_add_f32_e32 v54, 1.0, v54
	v_add_f32_e32 v55, 1.0, v55
	v_add_f32_e32 v48, 1.0, v48
	v_add_f32_e32 v49, 1.0, v49
	v_add_f32_e32 v50, 1.0, v50
	v_rcp_f32_e32 v51, v51
	v_rcp_f32_e32 v52, v52
	v_rcp_f32_e32 v53, v53
	v_rcp_f32_e32 v54, v54
	v_rcp_f32_e32 v55, v55
	v_rcp_f32_e32 v48, v48
	v_rcp_f32_e32 v49, v49
	v_rcp_f32_e32 v50, v50
	v_pk_add_f32 v[42:43], v[42:43], v[66:67]
	v_pk_add_f32 v[46:47], v[46:47], v[70:71]
	v_pk_add_f32 v[44:45], v[44:45], v[68:69]
	v_pk_add_f32 v[40:41], v[40:41], v[64:65]
	v_mul_f32_e32 v43, 0xbfb8aa3b, v43
	v_mul_f32_e32 v44, 0xbfb8aa3b, v44
	v_mul_f32_e32 v45, 0xbfb8aa3b, v45
	v_mul_f32_e32 v46, 0xbfb8aa3b, v46
	v_mul_f32_e32 v47, 0xbfb8aa3b, v47
	v_mul_f32_e32 v40, 0xbfb8aa3b, v40
	v_mul_f32_e32 v41, 0xbfb8aa3b, v41
	v_mul_f32_e32 v42, 0xbfb8aa3b, v42
	v_exp_f32_e32 v43, v43
	v_exp_f32_e32 v44, v44
	v_exp_f32_e32 v45, v45
	v_exp_f32_e32 v46, v46
	v_exp_f32_e32 v47, v47
	v_exp_f32_e32 v40, v40
	v_exp_f32_e32 v41, v41
	v_exp_f32_e32 v42, v42
	v_add_f32_e32 v43, 1.0, v43
	v_add_f32_e32 v44, 1.0, v44
	v_add_f32_e32 v45, 1.0, v45
	v_add_f32_e32 v46, 1.0, v46
	v_add_f32_e32 v47, 1.0, v47
	v_add_f32_e32 v40, 1.0, v40
	v_add_f32_e32 v41, 1.0, v41
	v_add_f32_e32 v42, 1.0, v42
	v_rcp_f32_e32 v43, v43
	v_rcp_f32_e32 v44, v44
	v_rcp_f32_e32 v45, v45
	v_rcp_f32_e32 v46, v46
	v_rcp_f32_e32 v47, v47
	v_rcp_f32_e32 v40, v40
	v_rcp_f32_e32 v41, v41
	v_rcp_f32_e32 v42, v42
	v_pk_add_f32 v[34:35], v[34:35], v[66:67]
	v_pk_add_f32 v[38:39], v[38:39], v[70:71]
	v_pk_add_f32 v[36:37], v[36:37], v[68:69]
	v_pk_add_f32 v[32:33], v[32:33], v[64:65]
	v_mul_f32_e32 v35, 0xbfb8aa3b, v35
	v_mul_f32_e32 v36, 0xbfb8aa3b, v36
	v_mul_f32_e32 v37, 0xbfb8aa3b, v37
	s_waitcnt vmcnt(7)
; __device__ __forceinline__ unsigned cvt_pk_bf16(float lo, float hi) { unsigned r; asm volatile("v_cvt_pk_bf16_f32 %0, %1, %2" : "=v"(r) : "v"(lo), "v"(hi)); return r; }
; __device__ __forceinline__ float bf_lo(unsigned w) { return __uint_as_float(w << 16); }
; __device__ __forceinline__ float bf_hi(unsigned w) { return __uint_as_float(w & 0xffff0000u); }
; __device__ __forceinline__ float sigmoid_f(float x) { return __builtin_amdgcn_rcpf(1.0f + __expf(-x)); }
; __device__ __forceinline__ float gelu_t(float x) { const float u = 1.5957691216057308f * (x + 0.044715f * x * x * x); return x * sigmoid_f(u); }
;     __device__ __forceinline__ void operator()(const f32x4 (&acc)[2][2][4][2], const Unit& u, int wr, int wc, int fr, int fq) const {
;     ...
;                     if (MODE == 1) { if (act) {
; #pragma unroll
;                         for (int j = 0; j < 4; ++j) { v0[j] = gelu_t(v0[j]); v1[j] = gelu_t(v1[j]); } } }
;                     if (MODE == 2) {
;                         const u32x4 y = *(const u32x4*)(Y + row * ldy + col);
;                         v0 = v0 + b0; v1 = v1 + b1;
;                         v0[0] = bf_lo(y.x) * sigmoid_f(v0[0]); v0[1] = bf_hi(y.x) * sigmoid_f(v0[1]); v0[2] = bf_lo(y.y) * sigmoid_f(v0[2]); v0[3] = bf_hi(y.y) * sigmoid_f(v0[3]);
;                         v1[0] = bf_lo(y.z) * sigmoid_f(v1[0]); v1[1] = bf_hi(y.z) * sigmoid_f(v1[1]); v1[2] = bf_lo(y.w) * sigmoid_f(v1[2]); v1[3] = bf_hi(y.w) * sigmoid_f(v1[3]);
;                     }
;                     u32x4 w; w.x = cvt_pk_bf16(v0[0], v0[1]); w.y = cvt_pk_bf16(v0[2], v0[3]); w.z = cvt_pk_bf16(v1[0], v1[1]); w.w = cvt_pk_bf16(v1[2], v1[3]);
;                     *(u32x4*)(O + row * ldc + col) = w;
	v_lshlrev_b32_e32 v63, 16, v193
	v_and_b32_e32 v59, 0xffff0000, v193
	v_lshlrev_b32_e32 v60, 16, v190
	v_and_b32_e32 v56, 0xffff0000, v190
	v_lshlrev_b32_e32 v61, 16, v191
	v_and_b32_e32 v57, 0xffff0000, v191
	v_lshlrev_b32_e32 v62, 16, v192
	v_and_b32_e32 v58, 0xffff0000, v192
	v_mul_f32_e32 v51, v51, v59
	v_mul_f32_e32 v52, v52, v60
	v_mul_f32_e32 v53, v53, v56
	v_mul_f32_e32 v54, v54, v61
	v_mul_f32_e32 v55, v55, v57
	v_mul_f32_e32 v56, v48, v62
	v_mul_f32_e32 v57, v49, v58
	v_mul_f32_e32 v58, v50, v63
	v_cvt_pk_bf16_f32 v48, v52, v53
	v_cvt_pk_bf16_f32 v49, v54, v55
	v_cvt_pk_bf16_f32 v50, v56, v57
	v_cvt_pk_bf16_f32 v51, v58, v51
	global_store_dwordx4 v[128:129], v[48:51], off offset:256
	v_mul_f32_e32 v38, 0xbfb8aa3b, v38
	v_mul_f32_e32 v39, 0xbfb8aa3b, v39
	v_mul_f32_e32 v32, 0xbfb8aa3b, v32
	v_mul_f32_e32 v33, 0xbfb8aa3b, v33
	v_mul_f32_e32 v34, 0xbfb8aa3b, v34
	v_exp_f32_e32 v35, v35
	v_exp_f32_e32 v36, v36
	v_exp_f32_e32 v37, v37
	v_exp_f32_e32 v38, v38
	v_exp_f32_e32 v39, v39
	v_exp_f32_e32 v32, v32
	v_exp_f32_e32 v33, v33
	v_exp_f32_e32 v34, v34
	v_add_f32_e32 v35, 1.0, v35
	v_add_f32_e32 v36, 1.0, v36
	v_add_f32_e32 v37, 1.0, v37
	v_add_f32_e32 v38, 1.0, v38
	v_add_f32_e32 v39, 1.0, v39
	v_add_f32_e32 v32, 1.0, v32
	v_add_f32_e32 v33, 1.0, v33
	v_add_f32_e32 v34, 1.0, v34
	v_rcp_f32_e32 v35, v35
	v_rcp_f32_e32 v36, v36
	v_rcp_f32_e32 v37, v37
	v_rcp_f32_e32 v38, v38
	v_rcp_f32_e32 v39, v39
	v_rcp_f32_e32 v32, v32
	v_rcp_f32_e32 v33, v33
	v_rcp_f32_e32 v34, v34
	v_pk_add_f32 v[26:27], v[26:27], v[66:67]
	v_pk_add_f32 v[30:31], v[30:31], v[70:71]
	v_pk_add_f32 v[28:29], v[28:29], v[68:69]
	v_pk_add_f32 v[24:25], v[24:25], v[64:65]
	v_mul_f32_e32 v27, 0xbfb8aa3b, v27
	v_mul_f32_e32 v28, 0xbfb8aa3b, v28
	v_mul_f32_e32 v29, 0xbfb8aa3b, v29
	v_mul_f32_e32 v30, 0xbfb8aa3b, v30
	v_mul_f32_e32 v31, 0xbfb8aa3b, v31
	v_mul_f32_e32 v24, 0xbfb8aa3b, v24
	v_mul_f32_e32 v25, 0xbfb8aa3b, v25
	v_mul_f32_e32 v26, 0xbfb8aa3b, v26
	v_exp_f32_e32 v27, v27
	v_exp_f32_e32 v28, v28
	v_exp_f32_e32 v29, v29
	v_exp_f32_e32 v30, v30
	v_exp_f32_e32 v31, v31
	v_exp_f32_e32 v24, v24
	v_exp_f32_e32 v25, v25
	v_exp_f32_e32 v26, v26
	v_add_f32_e32 v27, 1.0, v27
	v_add_f32_e32 v28, 1.0, v28
	v_add_f32_e32 v29, 1.0, v29
	v_add_f32_e32 v30, 1.0, v30
	v_add_f32_e32 v31, 1.0, v31
	v_add_f32_e32 v24, 1.0, v24
	v_add_f32_e32 v25, 1.0, v25
	v_add_f32_e32 v26, 1.0, v26
	v_rcp_f32_e32 v27, v27
	v_rcp_f32_e32 v28, v28
	v_rcp_f32_e32 v29, v29
	v_rcp_f32_e32 v30, v30
	v_rcp_f32_e32 v31, v31
	v_rcp_f32_e32 v24, v24
	v_rcp_f32_e32 v25, v25
	v_rcp_f32_e32 v26, v26
	v_pk_add_f32 v[18:19], v[18:19], v[66:67]
	v_pk_add_f32 v[22:23], v[22:23], v[70:71]
	v_pk_add_f32 v[20:21], v[20:21], v[68:69]
	v_pk_add_f32 v[16:17], v[16:17], v[64:65]
	v_mul_f32_e32 v19, 0xbfb8aa3b, v19
	v_mul_f32_e32 v20, 0xbfb8aa3b, v20
	v_mul_f32_e32 v21, 0xbfb8aa3b, v21
	v_mul_f32_e32 v22, 0xbfb8aa3b, v22
	v_mul_f32_e32 v23, 0xbfb8aa3b, v23
	v_mul_f32_e32 v16, 0xbfb8aa3b, v16
	v_mul_f32_e32 v17, 0xbfb8aa3b, v17
	v_mul_f32_e32 v18, 0xbfb8aa3b, v18
	v_exp_f32_e32 v19, v19
	v_exp_f32_e32 v20, v20
	s_waitcnt vmcnt(7)
	v_lshlrev_b32_e32 v55, 16, v197
	v_and_b32_e32 v51, 0xffff0000, v197
	v_lshlrev_b32_e32 v52, 16, v194
	v_and_b32_e32 v48, 0xffff0000, v194
	v_lshlrev_b32_e32 v53, 16, v195
	v_and_b32_e32 v49, 0xffff0000, v195
	v_lshlrev_b32_e32 v54, 16, v196
	v_and_b32_e32 v50, 0xffff0000, v196
	v_mul_f32_e32 v43, v43, v51
	v_mul_f32_e32 v44, v44, v52
	v_mul_f32_e32 v45, v45, v48
	v_mul_f32_e32 v46, v46, v53
	v_mul_f32_e32 v47, v47, v49
	v_mul_f32_e32 v48, v40, v54
	v_mul_f32_e32 v49, v41, v50
	v_mul_f32_e32 v50, v42, v55
	v_cvt_pk_bf16_f32 v40, v44, v45
	v_cvt_pk_bf16_f32 v41, v46, v47
	v_cvt_pk_bf16_f32 v42, v48, v49
	v_cvt_pk_bf16_f32 v43, v50, v43
	global_store_dwordx4 v[120:121], v[40:43], off offset:256
	v_exp_f32_e32 v21, v21
	v_exp_f32_e32 v22, v22
	v_exp_f32_e32 v23, v23
	v_exp_f32_e32 v16, v16
	v_exp_f32_e32 v17, v17
	v_exp_f32_e32 v18, v18
	v_add_f32_e32 v19, 1.0, v19
	v_add_f32_e32 v20, 1.0, v20
	v_add_f32_e32 v21, 1.0, v21
	v_add_f32_e32 v22, 1.0, v22
	v_add_f32_e32 v23, 1.0, v23
	v_add_f32_e32 v16, 1.0, v16
	v_add_f32_e32 v17, 1.0, v17
	v_add_f32_e32 v18, 1.0, v18
	v_rcp_f32_e32 v19, v19
	v_rcp_f32_e32 v20, v20
	v_rcp_f32_e32 v21, v21
	v_rcp_f32_e32 v22, v22
	v_rcp_f32_e32 v23, v23
	v_rcp_f32_e32 v16, v16
	v_rcp_f32_e32 v17, v17
	v_rcp_f32_e32 v18, v18
	v_pk_add_f32 v[10:11], v[10:11], v[66:67]
	v_pk_add_f32 v[14:15], v[14:15], v[70:71]
	v_pk_add_f32 v[12:13], v[12:13], v[68:69]
	v_pk_add_f32 v[8:9], v[8:9], v[64:65]
	v_mul_f32_e32 v11, 0xbfb8aa3b, v11
	v_mul_f32_e32 v12, 0xbfb8aa3b, v12
	v_mul_f32_e32 v13, 0xbfb8aa3b, v13
	v_mul_f32_e32 v14, 0xbfb8aa3b, v14
	v_mul_f32_e32 v15, 0xbfb8aa3b, v15
	v_mul_f32_e32 v8, 0xbfb8aa3b, v8
	v_mul_f32_e32 v9, 0xbfb8aa3b, v9
	v_mul_f32_e32 v10, 0xbfb8aa3b, v10
	v_exp_f32_e32 v11, v11
	v_exp_f32_e32 v12, v12
	v_exp_f32_e32 v13, v13
	v_exp_f32_e32 v14, v14
	v_exp_f32_e32 v15, v15
	v_exp_f32_e32 v8, v8
	v_exp_f32_e32 v9, v9
	v_exp_f32_e32 v10, v10
	v_add_f32_e32 v11, 1.0, v11
	v_add_f32_e32 v12, 1.0, v12
	v_add_f32_e32 v13, 1.0, v13
	v_add_f32_e32 v14, 1.0, v14
	v_add_f32_e32 v15, 1.0, v15
	v_add_f32_e32 v8, 1.0, v8
	v_add_f32_e32 v9, 1.0, v9
	v_add_f32_e32 v10, 1.0, v10
	v_rcp_f32_e32 v11, v11
	v_rcp_f32_e32 v12, v12
	v_rcp_f32_e32 v13, v13
	v_rcp_f32_e32 v14, v14
	v_rcp_f32_e32 v15, v15
	v_rcp_f32_e32 v8, v8
	v_rcp_f32_e32 v9, v9
	v_rcp_f32_e32 v10, v10
	v_pk_add_f32 v[2:3], v[2:3], v[66:67]
	v_pk_add_f32 v[6:7], v[6:7], v[70:71]
	v_pk_add_f32 v[4:5], v[4:5], v[68:69]
	v_pk_add_f32 v[0:1], v[0:1], v[64:65]
	v_mul_f32_e32 v3, 0xbfb8aa3b, v3
	v_mul_f32_e32 v4, 0xbfb8aa3b, v4
	v_mul_f32_e32 v5, 0xbfb8aa3b, v5
	v_mul_f32_e32 v6, 0xbfb8aa3b, v6
	v_mul_f32_e32 v7, 0xbfb8aa3b, v7
	v_mul_f32_e32 v0, 0xbfb8aa3b, v0
	v_mul_f32_e32 v1, 0xbfb8aa3b, v1
	v_mul_f32_e32 v2, 0xbfb8aa3b, v2
	v_exp_f32_e32 v3, v3
	v_exp_f32_e32 v4, v4
	v_exp_f32_e32 v5, v5
	v_exp_f32_e32 v6, v6
	v_exp_f32_e32 v7, v7
	v_exp_f32_e32 v0, v0
	v_exp_f32_e32 v1, v1
	v_exp_f32_e32 v2, v2
	v_add_f32_e32 v3, 1.0, v3
	s_waitcnt vmcnt(7)
; __device__ __forceinline__ unsigned cvt_pk_bf16(float lo, float hi) { unsigned r; asm volatile("v_cvt_pk_bf16_f32 %0, %1, %2" : "=v"(r) : "v"(lo), "v"(hi)); return r; }
; __device__ __forceinline__ float bf_lo(unsigned w) { return __uint_as_float(w << 16); }
; __device__ __forceinline__ float bf_hi(unsigned w) { return __uint_as_float(w & 0xffff0000u); }
; __device__ __forceinline__ float sigmoid_f(float x) { return __builtin_amdgcn_rcpf(1.0f + __expf(-x)); }
; __device__ __forceinline__ float gelu_t(float x) { const float u = 1.5957691216057308f * (x + 0.044715f * x * x * x); return x * sigmoid_f(u); }
;     __device__ __forceinline__ void operator()(const f32x4 (&acc)[2][2][4][2], const Unit& u, int wr, int wc, int fr, int fq) const {
;     ...
;                     if (MODE == 1) { if (act) {
; #pragma unroll
;                         for (int j = 0; j < 4; ++j) { v0[j] = gelu_t(v0[j]); v1[j] = gelu_t(v1[j]); } } }
;                     if (MODE == 2) {
;                         const u32x4 y = *(const u32x4*)(Y + row * ldy + col);
;                         v0 = v0 + b0; v1 = v1 + b1;
;                         v0[0] = bf_lo(y.x) * sigmoid_f(v0[0]); v0[1] = bf_hi(y.x) * sigmoid_f(v0[1]); v0[2] = bf_lo(y.y) * sigmoid_f(v0[2]); v0[3] = bf_hi(y.y) * sigmoid_f(v0[3]);
;                         v1[0] = bf_lo(y.z) * sigmoid_f(v1[0]); v1[1] = bf_hi(y.z) * sigmoid_f(v1[1]); v1[2] = bf_lo(y.w) * sigmoid_f(v1[2]); v1[3] = bf_hi(y.w) * sigmoid_f(v1[3]);
;                     }
;                     u32x4 w; w.x = cvt_pk_bf16(v0[0], v0[1]); w.y = cvt_pk_bf16(v0[2], v0[3]); w.z = cvt_pk_bf16(v1[0], v1[1]); w.w = cvt_pk_bf16(v1[2], v1[3]);
;                     *(u32x4*)(O + row * ldc + col) = w;
	v_lshlrev_b32_e32 v47, 16, v201
	v_and_b32_e32 v43, 0xffff0000, v201
	v_lshlrev_b32_e32 v44, 16, v198
	v_and_b32_e32 v40, 0xffff0000, v198
	v_lshlrev_b32_e32 v45, 16, v199
	v_and_b32_e32 v41, 0xffff0000, v199
	v_lshlrev_b32_e32 v46, 16, v200
	v_and_b32_e32 v42, 0xffff0000, v200
	v_mul_f32_e32 v35, v35, v43
	v_mul_f32_e32 v36, v36, v44
	v_mul_f32_e32 v37, v37, v40
	v_mul_f32_e32 v38, v38, v45
	v_mul_f32_e32 v39, v39, v41
	v_mul_f32_e32 v40, v32, v46
	v_mul_f32_e32 v41, v33, v42
	v_mul_f32_e32 v42, v34, v47
	v_cvt_pk_bf16_f32 v32, v36, v37
	v_cvt_pk_bf16_f32 v33, v38, v39
	v_cvt_pk_bf16_f32 v34, v40, v41
	v_cvt_pk_bf16_f32 v35, v42, v35
	global_store_dwordx4 v[104:105], v[32:35], off offset:256
	v_add_f32_e32 v4, 1.0, v4
	v_add_f32_e32 v5, 1.0, v5
	v_add_f32_e32 v6, 1.0, v6
	v_add_f32_e32 v7, 1.0, v7
	v_add_f32_e32 v0, 1.0, v0
	v_add_f32_e32 v1, 1.0, v1
	v_add_f32_e32 v2, 1.0, v2
	v_rcp_f32_e32 v3, v3
	v_rcp_f32_e32 v4, v4
	v_rcp_f32_e32 v5, v5
	v_rcp_f32_e32 v6, v6
	v_rcp_f32_e32 v7, v7
	v_rcp_f32_e32 v0, v0
	v_rcp_f32_e32 v1, v1
	v_rcp_f32_e32 v2, v2
	s_waitcnt vmcnt(7)
	v_lshlrev_b32_e32 v39, 16, v205
	v_and_b32_e32 v35, 0xffff0000, v205
	v_lshlrev_b32_e32 v36, 16, v202
	v_and_b32_e32 v32, 0xffff0000, v202
	v_lshlrev_b32_e32 v37, 16, v203
	v_and_b32_e32 v33, 0xffff0000, v203
	v_lshlrev_b32_e32 v38, 16, v204
	v_and_b32_e32 v34, 0xffff0000, v204
	v_mul_f32_e32 v27, v27, v35
	v_mul_f32_e32 v28, v28, v36
	v_mul_f32_e32 v29, v29, v32
	v_mul_f32_e32 v30, v30, v37
	v_mul_f32_e32 v31, v31, v33
	v_mul_f32_e32 v32, v24, v38
	v_mul_f32_e32 v33, v25, v34
	v_mul_f32_e32 v34, v26, v39
	v_cvt_pk_bf16_f32 v24, v28, v29
	v_cvt_pk_bf16_f32 v25, v30, v31
	v_cvt_pk_bf16_f32 v26, v32, v33
	v_cvt_pk_bf16_f32 v27, v34, v27
	global_store_dwordx4 v[96:97], v[24:27], off offset:256
	s_waitcnt vmcnt(7)
	v_lshlrev_b32_e32 v31, 16, v209
	v_and_b32_e32 v27, 0xffff0000, v209
	v_lshlrev_b32_e32 v28, 16, v206
	v_and_b32_e32 v24, 0xffff0000, v206
	v_lshlrev_b32_e32 v29, 16, v207
	v_and_b32_e32 v25, 0xffff0000, v207
	v_lshlrev_b32_e32 v30, 16, v208
	v_and_b32_e32 v26, 0xffff0000, v208
	v_mul_f32_e32 v19, v19, v27
	v_mul_f32_e32 v20, v20, v28
	v_mul_f32_e32 v21, v21, v24
	v_mul_f32_e32 v22, v22, v29
	v_mul_f32_e32 v23, v23, v25
	v_mul_f32_e32 v24, v16, v30
	v_mul_f32_e32 v25, v17, v26
	v_mul_f32_e32 v26, v18, v31
	v_cvt_pk_bf16_f32 v16, v20, v21
	v_cvt_pk_bf16_f32 v17, v22, v23
	v_cvt_pk_bf16_f32 v18, v24, v25
	v_cvt_pk_bf16_f32 v19, v26, v19
	global_store_dwordx4 v[88:89], v[16:19], off offset:256
	s_waitcnt vmcnt(7)
	v_lshlrev_b32_e32 v23, 16, v213
	v_and_b32_e32 v19, 0xffff0000, v213
	v_lshlrev_b32_e32 v20, 16, v210
	v_and_b32_e32 v16, 0xffff0000, v210
	v_lshlrev_b32_e32 v21, 16, v211
	v_and_b32_e32 v17, 0xffff0000, v211
	v_lshlrev_b32_e32 v22, 16, v212
	v_and_b32_e32 v18, 0xffff0000, v212
	v_mul_f32_e32 v11, v11, v19
	v_mul_f32_e32 v12, v12, v20
	v_mul_f32_e32 v13, v13, v16
	v_mul_f32_e32 v14, v14, v21
	v_mul_f32_e32 v15, v15, v17
	v_mul_f32_e32 v16, v8, v22
	v_mul_f32_e32 v17, v9, v18
	v_mul_f32_e32 v18, v10, v23
	v_cvt_pk_bf16_f32 v8, v12, v13
	v_cvt_pk_bf16_f32 v9, v14, v15
	v_cvt_pk_bf16_f32 v10, v16, v17
	v_cvt_pk_bf16_f32 v11, v18, v11
	global_store_dwordx4 v[80:81], v[8:11], off offset:256
	s_waitcnt vmcnt(7)
	v_lshlrev_b32_e32 v15, 16, v217
	v_and_b32_e32 v11, 0xffff0000, v217
	v_lshlrev_b32_e32 v12, 16, v214
	v_and_b32_e32 v8, 0xffff0000, v214
	v_lshlrev_b32_e32 v13, 16, v215
	v_and_b32_e32 v9, 0xffff0000, v215
	v_lshlrev_b32_e32 v14, 16, v216
	v_and_b32_e32 v10, 0xffff0000, v216
	v_mul_f32_e32 v3, v3, v11
	v_mul_f32_e32 v4, v4, v12
	v_mul_f32_e32 v5, v5, v8
	v_mul_f32_e32 v6, v6, v13
	v_mul_f32_e32 v7, v7, v9
	v_mul_f32_e32 v8, v0, v14
	v_mul_f32_e32 v9, v1, v10
	v_mul_f32_e32 v10, v2, v15
	v_cvt_pk_bf16_f32 v0, v4, v5
	v_cvt_pk_bf16_f32 v1, v6, v7
	v_cvt_pk_bf16_f32 v2, v8, v9
	v_cvt_pk_bf16_f32 v3, v10, v3
	global_store_dwordx4 v[72:73], v[0:3], off offset:256
	s_cbranch_vccnz .LBB0_752
	s_andn2_b64 vcc, exec, s[12:13]
	s_cbranch_vccnz .LBB0_751
	s_barrier
	s_branch .LBB0_751
